# nt policy on once-read loads: P3 ratio/SR and P6 residual
# speedup vs baseline: 1.0153x; 1.0016x over previous
.LBB0_780:
	s_cmpk_lg_i32 s64, 0x400
	s_cbranch_scc1 .LBB0_779
	v_mov_b32_e32 v4, v178
	v_mov_b32_e32 v184, v5
	v_lshl_add_u64 v[6:7], v[4:5], 1, s[44:45]
	v_lshl_add_u64 v[196:197], v[6:7], 0, v[148:149]
	global_load_dwordx4 v[196:199], v[196:197], off nt
	v_lshl_add_u64 v[200:201], v[6:7], 0, v[150:151]
	global_load_dwordx4 v[200:203], v[200:201], off nt
	s_mov_b64 s[26:27], 0x8000
	v_lshl_add_u64 v[204:205], v[6:7], 0, s[26:27]
	v_lshl_add_u64 v[206:207], v[204:205], 0, v[150:151]
	global_load_dwordx4 v[204:207], v[206:207], off nt
	s_mov_b64 s[26:27], 0x8000
	v_lshl_add_u64 v[208:209], v[6:7], 0, s[26:27]
	v_lshl_add_u64 v[208:209], v[208:209], 0, v[148:149]
	global_load_dwordx4 v[208:211], v[208:209], off nt
	s_mov_b64 s[26:27], 0x10000
	v_lshl_add_u64 v[212:213], v[6:7], 0, s[26:27]
	v_lshl_add_u64 v[214:215], v[212:213], 0, v[148:149]
	global_load_dwordx4 v[212:215], v[214:215], off nt
	s_mov_b64 s[26:27], 0x10000
	v_lshl_add_u64 v[216:217], v[6:7], 0, s[26:27]
	v_lshl_add_u64 v[218:219], v[216:217], 0, v[150:151]
	global_load_dwordx4 v[216:219], v[218:219], off nt
	v_lshl_add_u64 v[220:221], v[6:7], 0, s[14:15]
	v_lshl_add_u64 v[222:223], v[220:221], 0, v[150:151]
	global_load_dwordx4 v[220:223], v[222:223], off nt
	v_lshl_add_u64 v[224:225], v[6:7], 0, s[14:15]
	v_lshl_add_u64 v[224:225], v[224:225], 0, v[148:149]
	global_load_dwordx4 v[224:227], v[224:225], off nt
	s_mov_b64 s[26:27], 0x40000
	v_lshl_add_u64 v[228:229], v[6:7], 0, s[26:27]
	v_lshl_add_u64 v[230:231], v[228:229], 0, v[148:149]
	global_load_dwordx4 v[228:231], v[230:231], off nt
	s_mov_b64 s[26:27], 0x40000
	v_lshl_add_u64 v[232:233], v[6:7], 0, s[26:27]
	v_lshl_add_u64 v[234:235], v[232:233], 0, v[150:151]
	global_load_dwordx4 v[232:235], v[234:235], off nt
	s_mov_b64 s[26:27], 0x48000
	v_lshl_add_u64 v[236:237], v[6:7], 0, s[26:27]
	v_lshl_add_u64 v[238:239], v[236:237], 0, v[150:151]
	global_load_dwordx4 v[236:239], v[238:239], off nt
	s_mov_b64 s[26:27], 0x48000
	v_lshl_add_u64 v[240:241], v[6:7], 0, s[26:27]
	v_lshl_add_u64 v[240:241], v[240:241], 0, v[148:149]
	global_load_dwordx4 v[240:243], v[240:241], off nt
	v_lshl_add_u64 v[136:137], v[6:7], 0, v[148:149]
	v_lshl_add_u64 v[140:141], v[6:7], 0, v[150:151]
	v_mov_b32_e32 v182, v5
	v_mov_b32_e32 v183, v5
	v_mov_b32_e32 v185, v5
	s_mov_b64 s[26:27], 0x8000
	s_waitcnt vmcnt(10)
	v_cndmask_b32_e64 v180, v202, v198, s[8:9]
	v_cndmask_b32_e64 v138, v198, v202, s[8:9]
	v_cndmask_b32_e64 v4, v200, v196, s[8:9]
	v_cndmask_b32_e64 v179, v201, v197, s[8:9]
	v_cndmask_b32_e64 v136, v196, v200, s[8:9]
	v_cndmask_b32_e64 v137, v197, v201, s[8:9]
	v_mov_b32_dpp v184, v138 row_ror:8 row_mask:0xf bank_mask:0xf
	v_lshlrev_b32_e32 v140, 16, v180
	v_and_b32_e32 v141, 0xffff0000, v180
	v_cndmask_b32_e64 v181, v203, v199, s[8:9]
	v_cndmask_b32_e64 v139, v199, v203, s[8:9]
	s_mov_b64 s[26:27], 0x50000
	v_lshl_add_u64 v[196:197], v[6:7], 0, s[26:27]
	v_lshl_add_u64 v[198:199], v[196:197], 0, v[148:149]
	global_load_dwordx4 v[196:199], v[198:199], off nt
	s_mov_b64 s[26:27], 0x50000
	v_lshl_add_u64 v[200:201], v[6:7], 0, s[26:27]
	v_lshl_add_u64 v[202:203], v[200:201], 0, v[150:151]
	global_load_dwordx4 v[200:203], v[202:203], off nt
	v_mov_b32_dpp v182, v136 row_ror:8 row_mask:0xf bank_mask:0xf
	v_mov_b32_dpp v183, v137 row_ror:8 row_mask:0xf bank_mask:0xf
	v_lshlrev_b32_e32 v136, 16, v4
	v_and_b32_e32 v137, 0xffff0000, v4
	v_pk_mul_f32 v[128:129], v[128:129], v[140:141]
	v_lshlrev_b32_e32 v140, 16, v184
	v_and_b32_e32 v141, 0xffff0000, v184
	v_mov_b32_dpp v185, v139 row_ror:8 row_mask:0xf bank_mask:0xf
	v_lshlrev_b32_e32 v138, 16, v179
	v_and_b32_e32 v139, 0xffff0000, v179
	v_lshlrev_b32_e32 v142, 16, v181
	v_and_b32_e32 v143, 0xffff0000, v181
	v_pk_mul_f32 v[132:133], v[132:133], v[136:137]
	v_lshlrev_b32_e32 v136, 16, v182
	v_and_b32_e32 v137, 0xffff0000, v182
	v_pk_mul_f32 v[120:121], v[120:121], v[140:141]
	v_lshl_add_u64 v[140:141], v[6:7], 0, s[26:27]
	v_pk_mul_f32 v[134:135], v[134:135], v[138:139]
	v_pk_mul_f32 v[130:131], v[130:131], v[142:143]
	v_lshlrev_b32_e32 v138, 16, v183
	v_and_b32_e32 v139, 0xffff0000, v183
	v_lshlrev_b32_e32 v142, 16, v185
	v_and_b32_e32 v143, 0xffff0000, v185
	v_pk_mul_f32 v[124:125], v[124:125], v[136:137]
	v_lshl_add_u64 v[136:137], v[140:141], 0, v[150:151]
	v_lshl_add_u64 v[140:141], v[140:141], 0, v[148:149]
	v_pk_mul_f32 v[126:127], v[126:127], v[138:139]
	v_pk_mul_f32 v[122:123], v[122:123], v[142:143]
	v_mov_b32_e32 v182, v5
	v_mov_b32_e32 v183, v5
	v_mov_b32_e32 v184, v5
	v_mov_b32_e32 v185, v5
	s_mov_b64 s[26:27], 0x10000
	s_waitcnt vmcnt(10)
	v_cndmask_b32_e64 v4, v204, v208, s[8:9]
	v_cndmask_b32_e64 v179, v205, v209, s[8:9]
	v_cndmask_b32_e64 v136, v208, v204, s[8:9]
	v_cndmask_b32_e64 v137, v209, v205, s[8:9]
	v_cndmask_b32_e64 v180, v206, v210, s[8:9]
	v_cndmask_b32_e64 v181, v207, v211, s[8:9]
	v_cndmask_b32_e64 v138, v210, v206, s[8:9]
	v_cndmask_b32_e64 v139, v211, v207, s[8:9]
	s_mov_b64 s[26:27], 0x58000
	v_lshl_add_u64 v[204:205], v[6:7], 0, s[26:27]
	v_lshl_add_u64 v[206:207], v[204:205], 0, v[150:151]
	global_load_dwordx4 v[204:207], v[206:207], off nt
	s_mov_b64 s[26:27], 0x58000
	v_lshl_add_u64 v[208:209], v[6:7], 0, s[26:27]
	v_lshl_add_u64 v[208:209], v[208:209], 0, v[148:149]
	global_load_dwordx4 v[208:211], v[208:209], off nt
	v_mov_b32_dpp v182, v136 row_ror:8 row_mask:0xf bank_mask:0xf
	v_mov_b32_dpp v183, v137 row_ror:8 row_mask:0xf bank_mask:0xf
	v_lshlrev_b32_e32 v136, 16, v4
	v_and_b32_e32 v137, 0xffff0000, v4
	v_mov_b32_dpp v184, v138 row_ror:8 row_mask:0xf bank_mask:0xf
	v_mov_b32_dpp v185, v139 row_ror:8 row_mask:0xf bank_mask:0xf
	v_lshlrev_b32_e32 v138, 16, v179
	v_and_b32_e32 v139, 0xffff0000, v179
	v_lshlrev_b32_e32 v140, 16, v180
	v_and_b32_e32 v141, 0xffff0000, v180
	v_pk_mul_f32 v[116:117], v[116:117], v[136:137]
	v_lshlrev_b32_e32 v136, 16, v182
	v_and_b32_e32 v137, 0xffff0000, v182
	v_lshlrev_b32_e32 v142, 16, v181
	v_and_b32_e32 v143, 0xffff0000, v181
	v_pk_mul_f32 v[118:119], v[118:119], v[138:139]
	v_pk_mul_f32 v[112:113], v[112:113], v[140:141]
	v_lshlrev_b32_e32 v138, 16, v183
	v_and_b32_e32 v139, 0xffff0000, v183
	v_lshlrev_b32_e32 v140, 16, v184
	v_and_b32_e32 v141, 0xffff0000, v184
	v_pk_mul_f32 v[108:109], v[108:109], v[136:137]
	v_lshl_add_u64 v[136:137], v[6:7], 0, s[26:27]
	v_pk_mul_f32 v[114:115], v[114:115], v[142:143]
	v_lshlrev_b32_e32 v142, 16, v185
	v_and_b32_e32 v143, 0xffff0000, v185
	v_pk_mul_f32 v[110:111], v[110:111], v[138:139]
	v_pk_mul_f32 v[104:105], v[104:105], v[140:141]
	v_lshl_add_u64 v[138:139], v[136:137], 0, v[148:149]
	v_lshl_add_u64 v[140:141], v[136:137], 0, v[150:151]
	v_pk_mul_f32 v[106:107], v[106:107], v[142:143]
	v_mov_b32_e32 v184, v5
	v_mov_b32_e32 v182, v5
	v_mov_b32_e32 v183, v5
	v_mov_b32_e32 v185, v5
	s_mov_b64 s[26:27], 0x40000
	s_waitcnt vmcnt(10)
	v_cndmask_b32_e64 v180, v218, v214, s[8:9]
	v_cndmask_b32_e64 v138, v214, v218, s[8:9]
	v_cndmask_b32_e64 v4, v216, v212, s[8:9]
	v_cndmask_b32_e64 v179, v217, v213, s[8:9]
	v_cndmask_b32_e64 v136, v212, v216, s[8:9]
	v_cndmask_b32_e64 v137, v213, v217, s[8:9]
	v_mov_b32_dpp v184, v138 row_ror:8 row_mask:0xf bank_mask:0xf
	v_lshlrev_b32_e32 v140, 16, v180
	v_and_b32_e32 v141, 0xffff0000, v180
	v_cndmask_b32_e64 v181, v219, v215, s[8:9]
	v_cndmask_b32_e64 v139, v215, v219, s[8:9]
	v_mov_b32_dpp v182, v136 row_ror:8 row_mask:0xf bank_mask:0xf
	v_mov_b32_dpp v183, v137 row_ror:8 row_mask:0xf bank_mask:0xf
	v_lshlrev_b32_e32 v136, 16, v4
	v_and_b32_e32 v137, 0xffff0000, v4
	v_pk_mul_f32 v[96:97], v[96:97], v[140:141]
	v_lshlrev_b32_e32 v140, 16, v184
	v_and_b32_e32 v141, 0xffff0000, v184
	v_mov_b32_dpp v185, v139 row_ror:8 row_mask:0xf bank_mask:0xf
	v_lshlrev_b32_e32 v138, 16, v179
	v_and_b32_e32 v139, 0xffff0000, v179
	v_lshlrev_b32_e32 v142, 16, v181
	v_and_b32_e32 v143, 0xffff0000, v181
	v_pk_mul_f32 v[100:101], v[100:101], v[136:137]
	v_lshlrev_b32_e32 v136, 16, v182
	v_and_b32_e32 v137, 0xffff0000, v182
	v_pk_mul_f32 v[88:89], v[88:89], v[140:141]
	v_lshl_add_u64 v[140:141], v[6:7], 0, s[14:15]
	v_pk_mul_f32 v[102:103], v[102:103], v[138:139]
	v_pk_mul_f32 v[98:99], v[98:99], v[142:143]
	v_lshlrev_b32_e32 v138, 16, v183
	v_and_b32_e32 v139, 0xffff0000, v183
	v_lshlrev_b32_e32 v142, 16, v185
	v_and_b32_e32 v143, 0xffff0000, v185
	v_pk_mul_f32 v[92:93], v[92:93], v[136:137]
	v_lshl_add_u64 v[136:137], v[140:141], 0, v[150:151]
	v_lshl_add_u64 v[140:141], v[140:141], 0, v[148:149]
	v_pk_mul_f32 v[94:95], v[94:95], v[138:139]
	v_pk_mul_f32 v[90:91], v[90:91], v[142:143]
	v_mov_b32_e32 v182, v5
	v_mov_b32_e32 v183, v5
	v_mov_b32_e32 v184, v5
	v_mov_b32_e32 v185, v5
	s_waitcnt vmcnt(8)
	v_cndmask_b32_e64 v4, v220, v224, s[8:9]
	v_cndmask_b32_e64 v179, v221, v225, s[8:9]
	v_cndmask_b32_e64 v136, v224, v220, s[8:9]
	v_cndmask_b32_e64 v137, v225, v221, s[8:9]
	v_cndmask_b32_e64 v180, v222, v226, s[8:9]
	v_cndmask_b32_e64 v181, v223, v227, s[8:9]
	v_cndmask_b32_e64 v138, v226, v222, s[8:9]
	v_cndmask_b32_e64 v139, v227, v223, s[8:9]
	v_mov_b32_dpp v182, v136 row_ror:8 row_mask:0xf bank_mask:0xf
	v_mov_b32_dpp v183, v137 row_ror:8 row_mask:0xf bank_mask:0xf
	v_lshlrev_b32_e32 v136, 16, v4
	v_and_b32_e32 v137, 0xffff0000, v4
	v_mov_b32_dpp v184, v138 row_ror:8 row_mask:0xf bank_mask:0xf
	v_mov_b32_dpp v185, v139 row_ror:8 row_mask:0xf bank_mask:0xf
	v_lshlrev_b32_e32 v138, 16, v179
	v_and_b32_e32 v139, 0xffff0000, v179
	v_lshlrev_b32_e32 v140, 16, v180
	v_and_b32_e32 v141, 0xffff0000, v180
	v_pk_mul_f32 v[84:85], v[84:85], v[136:137]
	v_lshlrev_b32_e32 v136, 16, v182
	v_and_b32_e32 v137, 0xffff0000, v182
	v_lshlrev_b32_e32 v142, 16, v181
	v_and_b32_e32 v143, 0xffff0000, v181
	v_pk_mul_f32 v[86:87], v[86:87], v[138:139]
	v_pk_mul_f32 v[80:81], v[80:81], v[140:141]
	v_lshlrev_b32_e32 v138, 16, v183
	v_and_b32_e32 v139, 0xffff0000, v183
	v_lshlrev_b32_e32 v140, 16, v184
	v_and_b32_e32 v141, 0xffff0000, v184
	v_pk_mul_f32 v[76:77], v[76:77], v[136:137]
	v_lshl_add_u64 v[136:137], v[6:7], 0, s[26:27]
	v_pk_mul_f32 v[82:83], v[82:83], v[142:143]
	v_lshlrev_b32_e32 v142, 16, v185
	v_and_b32_e32 v143, 0xffff0000, v185
	v_pk_mul_f32 v[78:79], v[78:79], v[138:139]
	v_pk_mul_f32 v[72:73], v[72:73], v[140:141]
	v_lshl_add_u64 v[138:139], v[136:137], 0, v[148:149]
	v_lshl_add_u64 v[140:141], v[136:137], 0, v[150:151]
	v_pk_mul_f32 v[74:75], v[74:75], v[142:143]
	v_mov_b32_e32 v184, v5
	v_mov_b32_e32 v182, v5
	v_mov_b32_e32 v183, v5
	v_mov_b32_e32 v185, v5
	s_mov_b64 s[26:27], 0x48000
	s_waitcnt vmcnt(6)
	v_cndmask_b32_e64 v180, v234, v230, s[8:9]
	v_cndmask_b32_e64 v138, v230, v234, s[8:9]
	v_cndmask_b32_e64 v4, v232, v228, s[8:9]
	v_cndmask_b32_e64 v179, v233, v229, s[8:9]
	v_cndmask_b32_e64 v136, v228, v232, s[8:9]
	v_cndmask_b32_e64 v137, v229, v233, s[8:9]
	v_mov_b32_dpp v184, v138 row_ror:8 row_mask:0xf bank_mask:0xf
	v_lshlrev_b32_e32 v140, 16, v180
	v_and_b32_e32 v141, 0xffff0000, v180
	v_cndmask_b32_e64 v181, v235, v231, s[8:9]
	v_cndmask_b32_e64 v139, v231, v235, s[8:9]
	v_mov_b32_dpp v182, v136 row_ror:8 row_mask:0xf bank_mask:0xf
	v_mov_b32_dpp v183, v137 row_ror:8 row_mask:0xf bank_mask:0xf
	v_lshlrev_b32_e32 v136, 16, v4
	v_and_b32_e32 v137, 0xffff0000, v4
	v_pk_mul_f32 v[64:65], v[64:65], v[140:141]
	v_lshlrev_b32_e32 v140, 16, v184
	v_and_b32_e32 v141, 0xffff0000, v184
	v_mov_b32_dpp v185, v139 row_ror:8 row_mask:0xf bank_mask:0xf
	v_lshlrev_b32_e32 v138, 16, v179
	v_and_b32_e32 v139, 0xffff0000, v179
	v_lshlrev_b32_e32 v142, 16, v181
	v_and_b32_e32 v143, 0xffff0000, v181
	v_pk_mul_f32 v[68:69], v[68:69], v[136:137]
	v_lshlrev_b32_e32 v136, 16, v182
	v_and_b32_e32 v137, 0xffff0000, v182
	v_pk_mul_f32 v[56:57], v[56:57], v[140:141]
	v_lshl_add_u64 v[140:141], v[6:7], 0, s[26:27]
	v_pk_mul_f32 v[70:71], v[70:71], v[138:139]
	v_pk_mul_f32 v[66:67], v[66:67], v[142:143]
	v_lshlrev_b32_e32 v138, 16, v183
	v_and_b32_e32 v139, 0xffff0000, v183
	v_lshlrev_b32_e32 v142, 16, v185
	v_and_b32_e32 v143, 0xffff0000, v185
	v_pk_mul_f32 v[60:61], v[60:61], v[136:137]
	v_lshl_add_u64 v[136:137], v[140:141], 0, v[150:151]
	v_lshl_add_u64 v[140:141], v[140:141], 0, v[148:149]
	v_pk_mul_f32 v[62:63], v[62:63], v[138:139]
	v_pk_mul_f32 v[58:59], v[58:59], v[142:143]
	v_mov_b32_e32 v182, v5
	v_mov_b32_e32 v183, v5
	v_mov_b32_e32 v184, v5
	v_mov_b32_e32 v185, v5
	s_mov_b64 s[26:27], 0x50000
	s_waitcnt vmcnt(4)
	v_cndmask_b32_e64 v4, v236, v240, s[8:9]
	v_cndmask_b32_e64 v179, v237, v241, s[8:9]
	v_cndmask_b32_e64 v136, v240, v236, s[8:9]
	v_cndmask_b32_e64 v137, v241, v237, s[8:9]
	v_cndmask_b32_e64 v180, v238, v242, s[8:9]
	v_cndmask_b32_e64 v181, v239, v243, s[8:9]
	v_cndmask_b32_e64 v138, v242, v238, s[8:9]
	v_cndmask_b32_e64 v139, v243, v239, s[8:9]
	v_mov_b32_dpp v182, v136 row_ror:8 row_mask:0xf bank_mask:0xf
	v_mov_b32_dpp v183, v137 row_ror:8 row_mask:0xf bank_mask:0xf
	v_lshlrev_b32_e32 v136, 16, v4
	v_and_b32_e32 v137, 0xffff0000, v4
	v_mov_b32_dpp v184, v138 row_ror:8 row_mask:0xf bank_mask:0xf
	v_mov_b32_dpp v185, v139 row_ror:8 row_mask:0xf bank_mask:0xf
	v_lshlrev_b32_e32 v138, 16, v179
	v_and_b32_e32 v139, 0xffff0000, v179
	v_lshlrev_b32_e32 v140, 16, v180
	v_and_b32_e32 v141, 0xffff0000, v180
	v_pk_mul_f32 v[52:53], v[52:53], v[136:137]
	v_lshlrev_b32_e32 v136, 16, v182
	v_and_b32_e32 v137, 0xffff0000, v182
	v_lshlrev_b32_e32 v142, 16, v181
	v_and_b32_e32 v143, 0xffff0000, v181
	v_pk_mul_f32 v[54:55], v[54:55], v[138:139]
	v_pk_mul_f32 v[48:49], v[48:49], v[140:141]
	v_lshlrev_b32_e32 v138, 16, v183
	v_and_b32_e32 v139, 0xffff0000, v183
	v_lshlrev_b32_e32 v140, 16, v184
	v_and_b32_e32 v141, 0xffff0000, v184
	v_pk_mul_f32 v[44:45], v[44:45], v[136:137]
	v_lshl_add_u64 v[136:137], v[6:7], 0, s[26:27]
	v_pk_mul_f32 v[50:51], v[50:51], v[142:143]
	v_lshlrev_b32_e32 v142, 16, v185
	v_and_b32_e32 v143, 0xffff0000, v185
	v_pk_mul_f32 v[46:47], v[46:47], v[138:139]
	v_pk_mul_f32 v[40:41], v[40:41], v[140:141]
	v_lshl_add_u64 v[138:139], v[136:137], 0, v[148:149]
	v_lshl_add_u64 v[140:141], v[136:137], 0, v[150:151]
	v_pk_mul_f32 v[42:43], v[42:43], v[142:143]
	v_mov_b32_e32 v182, v5
	v_mov_b32_e32 v183, v5
	v_mov_b32_e32 v184, v5
	v_mov_b32_e32 v185, v5
	s_mov_b64 s[26:27], 0x58000
	v_lshl_add_u64 v[6:7], v[6:7], 0, s[26:27]
	s_waitcnt vmcnt(2)
	v_cndmask_b32_e64 v4, v200, v196, s[8:9]
	v_cndmask_b32_e64 v179, v201, v197, s[8:9]
	v_cndmask_b32_e64 v136, v196, v200, s[8:9]
	v_cndmask_b32_e64 v137, v197, v201, s[8:9]
	v_cndmask_b32_e64 v180, v202, v198, s[8:9]
	v_cndmask_b32_e64 v181, v203, v199, s[8:9]
	v_cndmask_b32_e64 v138, v198, v202, s[8:9]
	v_cndmask_b32_e64 v139, v199, v203, s[8:9]
	v_mov_b32_dpp v182, v136 row_ror:8 row_mask:0xf bank_mask:0xf
	v_mov_b32_dpp v183, v137 row_ror:8 row_mask:0xf bank_mask:0xf
	v_lshlrev_b32_e32 v136, 16, v4
	v_and_b32_e32 v137, 0xffff0000, v4
	v_mov_b32_dpp v184, v138 row_ror:8 row_mask:0xf bank_mask:0xf
	v_mov_b32_dpp v185, v139 row_ror:8 row_mask:0xf bank_mask:0xf
	v_lshlrev_b32_e32 v138, 16, v179
	v_and_b32_e32 v139, 0xffff0000, v179
	v_lshlrev_b32_e32 v140, 16, v180
	v_and_b32_e32 v141, 0xffff0000, v180
	v_lshlrev_b32_e32 v142, 16, v181
	v_and_b32_e32 v143, 0xffff0000, v181
	v_pk_mul_f32 v[36:37], v[36:37], v[136:137]
	v_lshlrev_b32_e32 v136, 16, v182
	v_and_b32_e32 v137, 0xffff0000, v182
	v_pk_mul_f32 v[38:39], v[38:39], v[138:139]
	v_pk_mul_f32 v[34:35], v[34:35], v[142:143]
	v_pk_mul_f32 v[32:33], v[32:33], v[140:141]
	v_lshlrev_b32_e32 v138, 16, v183
	v_and_b32_e32 v139, 0xffff0000, v183
	v_lshlrev_b32_e32 v140, 16, v184
	v_and_b32_e32 v141, 0xffff0000, v184
	v_lshlrev_b32_e32 v142, 16, v185
	v_and_b32_e32 v143, 0xffff0000, v185
	v_pk_mul_f32 v[28:29], v[28:29], v[136:137]
	v_lshl_add_u64 v[136:137], v[6:7], 0, v[150:151]
	v_lshl_add_u64 v[6:7], v[6:7], 0, v[148:149]
	v_pk_mul_f32 v[30:31], v[30:31], v[138:139]
	v_pk_mul_f32 v[26:27], v[26:27], v[142:143]
	v_pk_mul_f32 v[24:25], v[24:25], v[140:141]
	v_mov_b32_e32 v182, v5
	v_mov_b32_e32 v183, v5
	s_waitcnt vmcnt(0)
	v_cndmask_b32_e64 v4, v204, v208, s[8:9]
	v_cndmask_b32_e64 v179, v205, v209, s[8:9]
	v_cndmask_b32_e64 v180, v206, v210, s[8:9]
	v_cndmask_b32_e64 v181, v207, v211, s[8:9]
	v_cndmask_b32_e64 v6, v208, v204, s[8:9]
	v_cndmask_b32_e64 v7, v209, v205, s[8:9]
	v_cndmask_b32_e64 v136, v210, v206, s[8:9]
	v_cndmask_b32_e64 v137, v211, v207, s[8:9]
	v_mov_b32_e32 v142, v5
	v_mov_b32_e32 v143, v5
	v_mov_b32_dpp v182, v136 row_ror:8 row_mask:0xf bank_mask:0xf
	v_mov_b32_dpp v142, v6 row_ror:8 row_mask:0xf bank_mask:0xf
	v_mov_b32_dpp v143, v7 row_ror:8 row_mask:0xf bank_mask:0xf
	v_mov_b32_dpp v183, v137 row_ror:8 row_mask:0xf bank_mask:0xf
	v_lshlrev_b32_e32 v6, 16, v4
	v_and_b32_e32 v7, 0xffff0000, v4
	v_lshlrev_b32_e32 v136, 16, v179
	v_and_b32_e32 v137, 0xffff0000, v179
	v_lshlrev_b32_e32 v138, 16, v180
	v_and_b32_e32 v139, 0xffff0000, v180
	v_lshlrev_b32_e32 v140, 16, v181
	v_and_b32_e32 v141, 0xffff0000, v181
	v_pk_mul_f32 v[22:23], v[22:23], v[136:137]
	v_pk_mul_f32 v[20:21], v[20:21], v[6:7]
	v_pk_mul_f32 v[18:19], v[18:19], v[140:141]
	v_pk_mul_f32 v[16:17], v[16:17], v[138:139]
	v_lshlrev_b32_e32 v6, 16, v142
	v_and_b32_e32 v7, 0xffff0000, v142
	v_lshlrev_b32_e32 v136, 16, v143
	v_and_b32_e32 v137, 0xffff0000, v143
	v_lshlrev_b32_e32 v138, 16, v182
	v_and_b32_e32 v139, 0xffff0000, v182
	v_lshlrev_b32_e32 v140, 16, v183
	v_and_b32_e32 v141, 0xffff0000, v183
	v_pk_mul_f32 v[14:15], v[14:15], v[136:137]
	v_pk_mul_f32 v[12:13], v[12:13], v[6:7]
	v_pk_mul_f32 v[10:11], v[10:11], v[140:141]
	v_pk_mul_f32 v[8:9], v[8:9], v[138:139]
	s_branch .LBB0_779

.LBB0_784:
	v_lshl_add_u32 v136, s91, 8, v1
	v_or_b32_e32 v6, s92, v174
	v_ashrrev_i32_e32 v137, 31, v136
	v_ashrrev_i32_e32 v7, 31, v6
	v_lshlrev_b64 v[196:197], 10, v[136:137]
	v_lshl_add_u64 v[196:197], v[196:197], 0, v[6:7]
	v_lshlrev_b64 v[198:199], 1, v[196:197]
	v_lshl_add_u64 v[196:197], s[46:47], 0, v[198:199]
	v_lshl_add_u64 v[244:245], v[196:197], 0, v[148:149]
	global_load_dwordx4 v[196:199], v[244:245], off nt
	v_lshlrev_b64 v[200:201], 10, v[136:137]
	v_lshl_add_u64 v[200:201], v[200:201], 0, v[6:7]
	v_lshlrev_b64 v[202:203], 1, v[200:201]
	v_lshl_add_u64 v[200:201], s[46:47], 0, v[202:203]
	v_lshl_add_u64 v[244:245], v[200:201], 0, v[150:151]
	global_load_dwordx4 v[200:203], v[244:245], off nt
	v_or_b32_e32 v204, 16, v136
	v_ashrrev_i32_e32 v205, 31, v204
	v_lshlrev_b64 v[204:205], 10, v[204:205]
	v_lshl_add_u64 v[204:205], v[204:205], 0, v[6:7]
	v_lshlrev_b64 v[206:207], 1, v[204:205]
	v_lshl_add_u64 v[204:205], s[46:47], 0, v[206:207]
	v_lshl_add_u64 v[244:245], v[204:205], 0, v[148:149]
	global_load_dwordx4 v[204:207], v[244:245], off nt
	v_or_b32_e32 v208, 16, v136
	v_ashrrev_i32_e32 v209, 31, v208
	v_lshlrev_b64 v[208:209], 10, v[208:209]
	v_lshl_add_u64 v[208:209], v[208:209], 0, v[6:7]
	v_lshlrev_b64 v[210:211], 1, v[208:209]
	v_lshl_add_u64 v[208:209], s[46:47], 0, v[210:211]
	v_lshl_add_u64 v[244:245], v[208:209], 0, v[150:151]
	global_load_dwordx4 v[208:211], v[244:245], off nt
	v_or_b32_e32 v212, 32, v136
	v_ashrrev_i32_e32 v213, 31, v212
	v_lshlrev_b64 v[212:213], 10, v[212:213]
	v_lshl_add_u64 v[212:213], v[212:213], 0, v[6:7]
	v_lshlrev_b64 v[214:215], 1, v[212:213]
	v_lshl_add_u64 v[212:213], s[46:47], 0, v[214:215]
	v_lshl_add_u64 v[244:245], v[212:213], 0, v[148:149]
	global_load_dwordx4 v[212:215], v[244:245], off nt
	v_or_b32_e32 v216, 32, v136
	v_ashrrev_i32_e32 v217, 31, v216
	v_lshlrev_b64 v[216:217], 10, v[216:217]
	v_lshl_add_u64 v[216:217], v[216:217], 0, v[6:7]
	v_lshlrev_b64 v[218:219], 1, v[216:217]
	v_lshl_add_u64 v[216:217], s[46:47], 0, v[218:219]
	v_lshl_add_u64 v[244:245], v[216:217], 0, v[150:151]
	global_load_dwordx4 v[216:219], v[244:245], off nt
	v_or_b32_e32 v220, 48, v136
	v_ashrrev_i32_e32 v221, 31, v220
	v_lshlrev_b64 v[220:221], 10, v[220:221]
	v_lshl_add_u64 v[220:221], v[220:221], 0, v[6:7]
	v_lshlrev_b64 v[222:223], 1, v[220:221]
	v_lshl_add_u64 v[220:221], s[46:47], 0, v[222:223]
	v_lshl_add_u64 v[244:245], v[220:221], 0, v[148:149]
	global_load_dwordx4 v[220:223], v[244:245], off nt
	v_or_b32_e32 v224, 48, v136
	v_ashrrev_i32_e32 v225, 31, v224
	v_lshlrev_b64 v[224:225], 10, v[224:225]
	v_lshl_add_u64 v[224:225], v[224:225], 0, v[6:7]
	v_lshlrev_b64 v[226:227], 1, v[224:225]
	v_lshl_add_u64 v[224:225], s[46:47], 0, v[226:227]
	v_lshl_add_u64 v[244:245], v[224:225], 0, v[150:151]
	global_load_dwordx4 v[224:227], v[244:245], off nt
	v_lshlrev_b64 v[228:229], 10, v[136:137]
	v_lshl_add_u64 v[228:229], v[228:229], 0, v[6:7]
	v_lshl_add_u64 v[230:231], v[228:229], 1, v[162:163]
	v_lshl_add_u64 v[244:245], s[46:47], 0, v[230:231]
	v_lshl_add_u64 v[246:247], v[244:245], 0, v[148:149]
	global_load_dwordx4 v[228:231], v[246:247], off nt
	v_lshlrev_b64 v[232:233], 10, v[136:137]
	v_lshl_add_u64 v[232:233], v[232:233], 0, v[6:7]
	v_lshl_add_u64 v[234:235], v[232:233], 1, v[162:163]
	v_lshl_add_u64 v[244:245], s[46:47], 0, v[234:235]
	v_lshl_add_u64 v[246:247], v[244:245], 0, v[150:151]
	global_load_dwordx4 v[232:235], v[246:247], off nt
	v_lshlrev_b64 v[236:237], 10, v[136:137]
	v_lshl_add_u64 v[236:237], v[236:237], 0, v[6:7]
	v_lshl_add_u64 v[238:239], v[236:237], 1, v[164:165]
	v_lshl_add_u64 v[244:245], s[46:47], 0, v[238:239]
	v_lshl_add_u64 v[246:247], v[244:245], 0, v[148:149]
	global_load_dwordx4 v[236:239], v[246:247], off nt
	v_lshlrev_b64 v[240:241], 10, v[136:137]
	v_lshl_add_u64 v[240:241], v[240:241], 0, v[6:7]
	v_lshl_add_u64 v[242:243], v[240:241], 1, v[164:165]
	v_lshl_add_u64 v[244:245], s[46:47], 0, v[242:243]
	v_lshl_add_u64 v[246:247], v[244:245], 0, v[150:151]
	global_load_dwordx4 v[240:243], v[246:247], off nt
	v_lshlrev_b64 v[138:139], 10, v[136:137]
	v_lshl_add_u64 v[138:139], v[138:139], 0, v[6:7]
	v_lshlrev_b64 v[142:143], 1, v[138:139]
	v_lshl_add_u64 v[138:139], s[46:47], 0, v[142:143]
	v_lshl_add_u64 v[140:141], v[138:139], 0, v[148:149]
	v_lshl_add_u64 v[170:171], v[138:139], 0, v[150:151]
	v_mov_b32_e32 v183, v5
	v_mov_b32_e32 v184, v5
	s_waitcnt vmcnt(10)
	v_cndmask_b32_e64 v4, v200, v196, s[8:9]
	v_cndmask_b32_e64 v170, v201, v197, s[8:9]
	v_cndmask_b32_e64 v171, v202, v198, s[8:9]
	v_cndmask_b32_e64 v182, v203, v199, s[8:9]
	v_cndmask_b32_e64 v138, v196, v200, s[8:9]
	v_cndmask_b32_e64 v139, v197, v201, s[8:9]
	v_cndmask_b32_e64 v140, v198, v202, s[8:9]
	v_cndmask_b32_e64 v141, v199, v203, s[8:9]
	v_lshlrev_b64 v[196:197], 10, v[136:137]
	v_lshl_add_u64 v[198:199], v[196:197], 0, v[6:7]
	v_lshl_add_u64 v[244:245], v[198:199], 1, v[166:167]
	v_lshl_add_u64 v[196:197], s[46:47], 0, v[244:245]
	v_lshl_add_u64 v[246:247], v[196:197], 0, v[148:149]
	global_load_dwordx4 v[196:199], v[246:247], off nt
	v_lshlrev_b64 v[200:201], 10, v[136:137]
	v_lshl_add_u64 v[202:203], v[200:201], 0, v[6:7]
	v_lshl_add_u64 v[244:245], v[202:203], 1, v[166:167]
	v_lshl_add_u64 v[200:201], s[46:47], 0, v[244:245]
	v_lshl_add_u64 v[246:247], v[200:201], 0, v[150:151]
	global_load_dwordx4 v[200:203], v[246:247], off nt
	v_mov_b32_e32 v180, v5
	v_mov_b32_e32 v181, v5
	v_mov_b32_dpp v183, v140 row_ror:8 row_mask:0xf bank_mask:0xf
	v_mov_b32_dpp v180, v138 row_ror:8 row_mask:0xf bank_mask:0xf
	v_mov_b32_dpp v181, v139 row_ror:8 row_mask:0xf bank_mask:0xf
	v_mov_b32_dpp v184, v141 row_ror:8 row_mask:0xf bank_mask:0xf
	v_lshlrev_b32_e32 v138, 16, v4
	v_and_b32_e32 v139, 0xffff0000, v4
	v_lshlrev_b32_e32 v140, 16, v170
	v_and_b32_e32 v141, 0xffff0000, v170
	v_lshlrev_b32_e32 v170, 16, v171
	v_and_b32_e32 v171, 0xffff0000, v171
	v_lshlrev_b32_e32 v178, 16, v182
	v_and_b32_e32 v179, 0xffff0000, v182
	v_pk_mul_f32 v[134:135], v[134:135], v[140:141]
	v_pk_mul_f32 v[132:133], v[132:133], v[138:139]
	v_pk_mul_f32 v[130:131], v[130:131], v[178:179]
	v_pk_mul_f32 v[128:129], v[128:129], v[170:171]
	v_cvt_pk_bf16_f32 v4, v132, v133
	v_cvt_pk_bf16_f32 v132, v134, v135
	v_lshlrev_b32_e32 v138, 16, v183
	v_cvt_pk_bf16_f32 v133, v128, v129
	v_cvt_pk_bf16_f32 v134, v130, v131
	v_lshlrev_b32_e32 v128, 16, v180
	v_and_b32_e32 v129, 0xffff0000, v180
	v_lshlrev_b32_e32 v130, 16, v181
	v_and_b32_e32 v131, 0xffff0000, v181
	v_and_b32_e32 v139, 0xffff0000, v183
	v_lshlrev_b32_e32 v140, 16, v184
	v_and_b32_e32 v141, 0xffff0000, v184
	v_pk_mul_f32 v[126:127], v[126:127], v[130:131]
	v_pk_mul_f32 v[124:125], v[124:125], v[128:129]
	v_pk_mul_f32 v[122:123], v[122:123], v[140:141]
	v_pk_mul_f32 v[120:121], v[120:121], v[138:139]
	v_cvt_pk_bf16_f32 v124, v124, v125
	v_cvt_pk_bf16_f32 v125, v126, v127
	v_lshl_add_u64 v[128:129], s[40:41], 0, v[142:143]
	v_cvt_pk_bf16_f32 v126, v120, v121
	v_cvt_pk_bf16_f32 v127, v122, v123
	v_mov_b32_e32 v120, v5
	v_mov_b32_e32 v121, v5
	v_mov_b32_e32 v122, v5
	v_mov_b32_e32 v123, v5
	v_mov_b32_dpp v120, v124 row_ror:8 row_mask:0xf bank_mask:0xf
	v_mov_b32_dpp v121, v125 row_ror:8 row_mask:0xf bank_mask:0xf
	v_mov_b32_dpp v122, v126 row_ror:8 row_mask:0xf bank_mask:0xf
	v_mov_b32_dpp v123, v127 row_ror:8 row_mask:0xf bank_mask:0xf
	v_lshl_add_u64 v[130:131], v[128:129], 0, s[58:59]
	v_mov_b32_e32 v124, v4
	v_mov_b32_e32 v125, v132
	v_mov_b32_e32 v126, v133
	v_mov_b32_e32 v127, v134
	s_and_saveexec_b64 s[26:27], s[8:9]
	s_cbranch_execz .LBB0_786
	v_lshl_add_u64 v[138:139], v[128:129], 0, s[60:61]
	v_mov_b64_e32 v[130:131], v[128:129]
	v_mov_b32_e32 v124, v120
	v_mov_b32_e32 v125, v121
	v_mov_b32_e32 v126, v122
	v_mov_b32_e32 v127, v123
	v_mov_b32_e32 v120, v4
	v_mov_b32_e32 v121, v132
	v_mov_b32_e32 v122, v133
	v_mov_b32_e32 v123, v134
	v_mov_b64_e32 v[128:129], v[138:139]
.LBB0_786:
	s_or_b64 exec, exec, s[26:27]
	global_store_dwordx4 v[130:131], v[120:123], off
	global_store_dwordx4 v[128:129], v[124:127], off
	v_mov_b32_e32 v133, v5
	v_or_b32_e32 v120, 16, v136
	v_ashrrev_i32_e32 v121, 31, v120
	v_lshlrev_b64 v[120:121], 10, v[120:121]
	v_lshl_add_u64 v[120:121], v[120:121], 0, v[6:7]
	v_lshlrev_b64 v[128:129], 1, v[120:121]
	v_lshl_add_u64 v[120:121], s[46:47], 0, v[128:129]
	v_lshl_add_u64 v[122:123], v[120:121], 0, v[148:149]
	v_lshl_add_u64 v[124:125], v[120:121], 0, v[150:151]
	v_mov_b32_e32 v134, v5
	v_mov_b32_e32 v135, v5
	v_mov_b32_e32 v138, v5
	s_waitcnt vmcnt(12)
	v_cndmask_b32_e64 v4, v208, v204, s[8:9]
	v_cndmask_b32_e64 v130, v209, v205, s[8:9]
	v_cndmask_b32_e64 v131, v210, v206, s[8:9]
	v_cndmask_b32_e64 v132, v211, v207, s[8:9]
	v_cndmask_b32_e64 v120, v204, v208, s[8:9]
	v_cndmask_b32_e64 v121, v205, v209, s[8:9]
	v_cndmask_b32_e64 v122, v206, v210, s[8:9]
	v_cndmask_b32_e64 v123, v207, v211, s[8:9]
	v_lshlrev_b64 v[204:205], 10, v[136:137]
	v_lshl_add_u64 v[206:207], v[204:205], 0, v[6:7]
	v_lshl_add_u64 v[206:207], v[206:207], 1, v[168:169]
	v_lshl_add_u64 v[244:245], s[46:47], 0, v[206:207]
	v_lshl_add_u64 v[246:247], v[244:245], 0, v[148:149]
	global_load_dwordx4 v[204:207], v[246:247], off nt
	v_lshlrev_b64 v[208:209], 10, v[136:137]
	v_lshl_add_u64 v[210:211], v[208:209], 0, v[6:7]
	v_lshl_add_u64 v[210:211], v[210:211], 1, v[168:169]
	v_lshl_add_u64 v[244:245], s[46:47], 0, v[210:211]
	v_lshl_add_u64 v[246:247], v[244:245], 0, v[150:151]
	global_load_dwordx4 v[208:211], v[246:247], off nt
	v_mov_b32_dpp v133, v120 row_ror:8 row_mask:0xf bank_mask:0xf
	v_mov_b32_dpp v134, v121 row_ror:8 row_mask:0xf bank_mask:0xf
	v_mov_b32_dpp v135, v122 row_ror:8 row_mask:0xf bank_mask:0xf
	v_mov_b32_dpp v138, v123 row_ror:8 row_mask:0xf bank_mask:0xf
	v_lshlrev_b32_e32 v120, 16, v4
	v_and_b32_e32 v121, 0xffff0000, v4
	v_lshlrev_b32_e32 v122, 16, v130
	v_and_b32_e32 v123, 0xffff0000, v130
	v_lshlrev_b32_e32 v124, 16, v131
	v_and_b32_e32 v125, 0xffff0000, v131
	v_lshlrev_b32_e32 v126, 16, v132
	v_and_b32_e32 v127, 0xffff0000, v132
	v_pk_mul_f32 v[118:119], v[118:119], v[122:123]
	v_pk_mul_f32 v[116:117], v[116:117], v[120:121]
	v_pk_mul_f32 v[114:115], v[114:115], v[126:127]
	v_pk_mul_f32 v[112:113], v[112:113], v[124:125]
	v_cvt_pk_bf16_f32 v4, v116, v117
	v_cvt_pk_bf16_f32 v116, v118, v119
	v_lshlrev_b32_e32 v120, 16, v135
	v_cvt_pk_bf16_f32 v117, v112, v113
	v_cvt_pk_bf16_f32 v118, v114, v115
	v_lshlrev_b32_e32 v112, 16, v133
	v_and_b32_e32 v113, 0xffff0000, v133
	v_lshlrev_b32_e32 v114, 16, v134
	v_and_b32_e32 v115, 0xffff0000, v134
	v_and_b32_e32 v121, 0xffff0000, v135
	v_lshlrev_b32_e32 v122, 16, v138
	v_and_b32_e32 v123, 0xffff0000, v138
	v_pk_mul_f32 v[110:111], v[110:111], v[114:115]
	v_pk_mul_f32 v[108:109], v[108:109], v[112:113]
	v_pk_mul_f32 v[106:107], v[106:107], v[122:123]
	v_pk_mul_f32 v[104:105], v[104:105], v[120:121]
	v_cvt_pk_bf16_f32 v108, v108, v109
	v_cvt_pk_bf16_f32 v109, v110, v111
	v_lshl_add_u64 v[112:113], s[40:41], 0, v[128:129]
	v_cvt_pk_bf16_f32 v110, v104, v105
	v_cvt_pk_bf16_f32 v111, v106, v107
	v_mov_b32_e32 v104, v5
	v_mov_b32_e32 v105, v5
	v_mov_b32_e32 v106, v5
	v_mov_b32_e32 v107, v5
	v_mov_b32_dpp v104, v108 row_ror:8 row_mask:0xf bank_mask:0xf
	v_mov_b32_dpp v105, v109 row_ror:8 row_mask:0xf bank_mask:0xf
	v_mov_b32_dpp v106, v110 row_ror:8 row_mask:0xf bank_mask:0xf
	v_mov_b32_dpp v107, v111 row_ror:8 row_mask:0xf bank_mask:0xf
	v_lshl_add_u64 v[114:115], v[112:113], 0, s[58:59]
	v_mov_b32_e32 v108, v4
	v_mov_b32_e32 v109, v116
	v_mov_b32_e32 v110, v117
	v_mov_b32_e32 v111, v118
	s_and_saveexec_b64 s[26:27], s[8:9]
	s_cbranch_execz .LBB0_788
	v_lshl_add_u64 v[120:121], v[112:113], 0, s[60:61]
	v_mov_b64_e32 v[114:115], v[112:113]
	v_mov_b32_e32 v108, v104
	v_mov_b32_e32 v109, v105
	v_mov_b32_e32 v110, v106
	v_mov_b32_e32 v111, v107
	v_mov_b32_e32 v104, v4
	v_mov_b32_e32 v105, v116
	v_mov_b32_e32 v106, v117
	v_mov_b32_e32 v107, v118
	v_mov_b64_e32 v[112:113], v[120:121]

.LBB0_1376:
	s_lshl_b32 s18, s8, 8
	s_add_i32 s2, s18, s62
	v_or_b32_e32 v166, s2, v3
	s_lshl_b32 s2, s0, 8
	s_lshl_b32 s3, s9, 6
	s_or_b32 s2, s2, s3
	v_ashrrev_i32_e32 v167, 31, v166
	v_lshl_or_b32 v0, v142, 3, s2
	v_cmp_gt_u32_e64 s[2:3], 8, v3
	v_mov_b32_e32 v3, 0xffffc040
	v_lshlrev_b64 v[132:133], 11, v[166:167]
	v_ashrrev_i32_e32 v1, 31, v0
	v_cndmask_b32_e64 v162, v3, 0, s[2:3]
	v_mov_b32_e32 v3, 0x4040
	v_lshl_add_u64 v[132:133], s[42:43], 0, v[132:133]
	v_cndmask_b32_e64 v163, -1, 0, s[2:3]
	v_cndmask_b32_e64 v164, 0, v3, s[2:3]
	v_mov_b32_e32 v165, 0
	v_lshl_add_u64 v[132:133], v[0:1], 1, v[132:133]
	v_lshl_add_u64 v[134:135], v[132:133], 0, v[162:163]
	v_lshl_add_u64 v[136:137], v[132:133], 0, v[164:165]
	s_barrier
	global_load_dwordx4 v[132:135], v[134:135], off nt
	s_nop 0
	global_load_dwordx4 v[136:139], v[136:137], off nt
	v_mbcnt_lo_u32_b32 v3, -1, 0
	v_mbcnt_hi_u32_b32 v3, -1, v3
	v_and_b32_e32 v145, 64, v3
	v_xor_b32_e32 v144, 16, v3
	v_add_u32_e32 v170, 64, v145
	v_cmp_lt_i32_e32 vcc, v144, v170
	v_mov_b32_e32 v140, v165
	v_mov_b32_e32 v141, v165
	v_cndmask_b32_e32 v144, v3, v144, vcc
	v_lshlrev_b32_e32 v169, 2, v144
	v_mov_b32_e32 v142, v165
	v_mov_b32_e32 v143, v165
	s_lshl_b32 s4, s9, 2
	s_add_i32 s6, s4, 0x100
	s_waitcnt vmcnt(0)
	v_cndmask_b32_e64 v144, v136, v132, s[2:3]
	v_cndmask_b32_e64 v145, v137, v133, s[2:3]
	v_cndmask_b32_e64 v146, v138, v134, s[2:3]
	v_cndmask_b32_e64 v147, v139, v135, s[2:3]
	v_cndmask_b32_e64 v132, v132, v136, s[2:3]
	v_cndmask_b32_e64 v133, v133, v137, s[2:3]
	v_cndmask_b32_e64 v134, v134, v138, s[2:3]
	v_cndmask_b32_e64 v135, v135, v139, s[2:3]
	v_mov_b32_dpp v140, v132 row_ror:8 row_mask:0xf bank_mask:0xf
	v_mov_b32_dpp v141, v133 row_ror:8 row_mask:0xf bank_mask:0xf
	v_lshlrev_b32_e32 v136, 16, v146
	v_and_b32_e32 v137, 0xffff0000, v146
	v_lshlrev_b32_e32 v138, 16, v147
	v_and_b32_e32 v139, 0xffff0000, v147
	v_mov_b32_dpp v142, v134 row_ror:8 row_mask:0xf bank_mask:0xf
	v_mov_b32_dpp v143, v135 row_ror:8 row_mask:0xf bank_mask:0xf
	v_lshlrev_b32_e32 v132, 16, v144
	v_and_b32_e32 v133, 0xffff0000, v144
	v_lshlrev_b32_e32 v134, 16, v145
	v_and_b32_e32 v135, 0xffff0000, v145
	v_pk_add_f32 v[152:153], v[126:127], v[138:139]
	v_pk_add_f32 v[154:155], v[124:125], v[136:137]
	v_lshlrev_b32_e32 v124, 16, v140
	v_and_b32_e32 v125, 0xffff0000, v140
	v_lshlrev_b32_e32 v126, 16, v141
	v_and_b32_e32 v127, 0xffff0000, v141
	v_pk_add_f32 v[158:159], v[130:131], v[134:135]
	v_pk_add_f32 v[160:161], v[128:129], v[132:133]
	v_lshlrev_b32_e32 v128, 16, v142
	v_and_b32_e32 v129, 0xffff0000, v142
	v_pk_add_f32 v[148:149], v[122:123], v[126:127]
	v_pk_add_f32 v[150:151], v[120:121], v[124:125]
	v_lshlrev_b32_e32 v130, 16, v143
	v_and_b32_e32 v131, 0xffff0000, v143
	v_mul_f32_e32 v132, v161, v161
	v_mul_f32_e32 v133, v159, v159
	v_pk_add_f32 v[146:147], v[116:117], v[128:129]
	v_mul_f32_e32 v116, v151, v151
	v_mul_f32_e32 v117, v149, v149
	v_mul_f32_e32 v134, v155, v155
	v_pk_add_f32 v[144:145], v[118:119], v[130:131]
	v_fmac_f32_e32 v132, v160, v160
	v_fmac_f32_e32 v133, v158, v158
	v_mul_f32_e32 v118, v147, v147
	v_fmac_f32_e32 v116, v150, v150
	v_fmac_f32_e32 v117, v148, v148
	v_mul_f32_e32 v135, v153, v153
	v_fmac_f32_e32 v134, v154, v154
	v_mul_f32_e32 v119, v145, v145
	v_add_f32_e32 v120, v132, v133
	v_fmac_f32_e32 v118, v146, v146
	v_add_f32_e32 v116, v116, v117
	v_fmac_f32_e32 v135, v152, v152
	v_add_f32_e32 v120, v134, v120
	v_add_f32_e32 v116, v116, v118
	v_fmac_f32_e32 v119, v144, v144
	v_add_f32_e32 v117, v135, v120
	v_add_f32_e32 v116, v119, v116
	v_add_f32_e32 v116, v116, v117
	ds_bpermute_b32 v117, v169, v116
	v_xor_b32_e32 v118, 32, v3
	v_cmp_lt_i32_e32 vcc, v118, v170
	v_lshl_add_u32 v170, v168, 4, s6
	s_nop 0
	v_cndmask_b32_e32 v3, v3, v118, vcc
	v_lshlrev_b32_e32 v171, 2, v3
	s_waitcnt lgkmcnt(0)
	v_add_f32_e32 v3, v116, v117
	ds_bpermute_b32 v116, v171, v3
	v_cmp_gt_u32_e32 vcc, 16, v157
	s_and_saveexec_b64 s[4:5], vcc
	v_readlane_b32 s22, v254, 13
	v_readlane_b32 s23, v254, 14
	s_cbranch_execz .LBB0_1378
	s_waitcnt lgkmcnt(0)
	v_add_f32_e32 v3, v3, v116
	ds_write_b32 v170, v3
.LBB0_1378:
	s_or_b64 exec, exec, s[4:5]
	s_waitcnt lgkmcnt(0)
	v_or_b32_e32 v116, 16, v166
	v_ashrrev_i32_e32 v117, 31, v116
	v_lshlrev_b64 v[116:117], 11, v[116:117]
	v_lshl_add_u64 v[116:117], s[42:43], 0, v[116:117]
	v_lshl_add_u64 v[116:117], v[0:1], 1, v[116:117]
	v_lshl_add_u64 v[118:119], v[116:117], 0, v[162:163]
	v_lshl_add_u64 v[120:121], v[116:117], 0, v[164:165]
	global_load_dwordx4 v[116:119], v[118:119], off nt
	s_nop 0
	global_load_dwordx4 v[120:123], v[120:121], off nt
	v_mov_b32_e32 v3, v165
	v_mov_b32_e32 v124, v165
	v_mov_b32_e32 v125, v165
	v_mov_b32_e32 v126, v165
	s_waitcnt vmcnt(0)
	v_cndmask_b32_e64 v127, v120, v116, s[2:3]
	v_cndmask_b32_e64 v128, v121, v117, s[2:3]
	v_cndmask_b32_e64 v129, v122, v118, s[2:3]
	v_cndmask_b32_e64 v130, v123, v119, s[2:3]
	v_cndmask_b32_e64 v116, v116, v120, s[2:3]
	v_cndmask_b32_e64 v117, v117, v121, s[2:3]
	v_cndmask_b32_e64 v118, v118, v122, s[2:3]
	v_cndmask_b32_e64 v119, v119, v123, s[2:3]
	v_mov_b32_dpp v3, v116 row_ror:8 row_mask:0xf bank_mask:0xf
	v_mov_b32_dpp v124, v117 row_ror:8 row_mask:0xf bank_mask:0xf
	v_lshlrev_b32_e32 v120, 16, v129
	v_and_b32_e32 v121, 0xffff0000, v129
	v_lshlrev_b32_e32 v122, 16, v130
	v_and_b32_e32 v123, 0xffff0000, v130
	v_mov_b32_dpp v125, v118 row_ror:8 row_mask:0xf bank_mask:0xf
	v_mov_b32_dpp v126, v119 row_ror:8 row_mask:0xf bank_mask:0xf
	v_lshlrev_b32_e32 v116, 16, v127
	v_and_b32_e32 v117, 0xffff0000, v127
	v_lshlrev_b32_e32 v118, 16, v128
	v_and_b32_e32 v119, 0xffff0000, v128
	v_pk_add_f32 v[136:137], v[110:111], v[122:123]
	v_pk_add_f32 v[138:139], v[108:109], v[120:121]
	v_lshlrev_b32_e32 v108, 16, v3
	v_and_b32_e32 v109, 0xffff0000, v3
	v_lshlrev_b32_e32 v110, 16, v124
	v_and_b32_e32 v111, 0xffff0000, v124
	v_pk_add_f32 v[140:141], v[114:115], v[118:119]
	v_pk_add_f32 v[142:143], v[112:113], v[116:117]
	v_lshlrev_b32_e32 v112, 16, v125
	v_and_b32_e32 v113, 0xffff0000, v125
	v_pk_add_f32 v[132:133], v[106:107], v[110:111]
	v_pk_add_f32 v[134:135], v[104:105], v[108:109]
	v_lshlrev_b32_e32 v114, 16, v126
	v_and_b32_e32 v115, 0xffff0000, v126
	v_mul_f32_e32 v3, v143, v143
	v_mul_f32_e32 v116, v141, v141
	v_pk_add_f32 v[130:131], v[100:101], v[112:113]
	v_mul_f32_e32 v100, v135, v135
	v_mul_f32_e32 v101, v133, v133
	v_mul_f32_e32 v117, v139, v139
	v_pk_add_f32 v[126:127], v[102:103], v[114:115]
	v_fmac_f32_e32 v3, v142, v142
	v_fmac_f32_e32 v116, v140, v140
	v_mul_f32_e32 v102, v131, v131
	v_fmac_f32_e32 v100, v134, v134
	v_fmac_f32_e32 v101, v132, v132
	v_mul_f32_e32 v118, v137, v137
	v_fmac_f32_e32 v117, v138, v138
	v_mul_f32_e32 v103, v127, v127
	v_add_f32_e32 v3, v3, v116
	v_fmac_f32_e32 v102, v130, v130
	v_add_f32_e32 v100, v100, v101
	v_fmac_f32_e32 v118, v136, v136
	v_add_f32_e32 v3, v117, v3
	v_add_f32_e32 v100, v100, v102
	v_fmac_f32_e32 v103, v126, v126
	v_add_f32_e32 v3, v118, v3
	v_add_f32_e32 v100, v103, v100
	v_add_f32_e32 v3, v100, v3
	ds_bpermute_b32 v100, v169, v3
	s_waitcnt lgkmcnt(0)
	v_add_f32_e32 v3, v3, v100
	ds_bpermute_b32 v100, v171, v3
	s_and_saveexec_b64 s[4:5], vcc
	s_cbranch_execz .LBB0_1380
	s_waitcnt lgkmcnt(0)
	v_add_f32_e32 v3, v3, v100
	ds_write_b32 v170, v3 offset:256
.LBB0_1380:
	s_or_b64 exec, exec, s[4:5]
	s_waitcnt lgkmcnt(0)
	v_or_b32_e32 v100, 32, v166
	v_ashrrev_i32_e32 v101, 31, v100
	v_lshlrev_b64 v[100:101], 11, v[100:101]
	v_lshl_add_u64 v[100:101], s[42:43], 0, v[100:101]
	v_lshl_add_u64 v[100:101], v[0:1], 1, v[100:101]
	v_lshl_add_u64 v[102:103], v[100:101], 0, v[162:163]
	v_lshl_add_u64 v[104:105], v[100:101], 0, v[164:165]
	global_load_dwordx4 v[100:103], v[102:103], off nt
	s_nop 0
	global_load_dwordx4 v[104:107], v[104:105], off nt
	v_mov_b32_e32 v3, 0
	v_mov_b32_e32 v108, 0
	v_mov_b32_e32 v109, 0
	v_mov_b32_e32 v110, 0
	s_waitcnt vmcnt(0)
	v_cndmask_b32_e64 v111, v104, v100, s[2:3]
	v_cndmask_b32_e64 v112, v105, v101, s[2:3]
	v_cndmask_b32_e64 v113, v106, v102, s[2:3]
	v_cndmask_b32_e64 v114, v107, v103, s[2:3]
	v_cndmask_b32_e64 v100, v100, v104, s[2:3]
	v_cndmask_b32_e64 v101, v101, v105, s[2:3]
	v_cndmask_b32_e64 v102, v102, v106, s[2:3]
	v_cndmask_b32_e64 v103, v103, v107, s[2:3]
	v_mov_b32_dpp v3, v100 row_ror:8 row_mask:0xf bank_mask:0xf
	v_mov_b32_dpp v108, v101 row_ror:8 row_mask:0xf bank_mask:0xf
	v_lshlrev_b32_e32 v104, 16, v113
	v_and_b32_e32 v105, 0xffff0000, v113
	v_lshlrev_b32_e32 v106, 16, v114
	v_and_b32_e32 v107, 0xffff0000, v114
	v_mov_b32_dpp v109, v102 row_ror:8 row_mask:0xf bank_mask:0xf
	v_mov_b32_dpp v110, v103 row_ror:8 row_mask:0xf bank_mask:0xf
	v_lshlrev_b32_e32 v100, 16, v111
	v_and_b32_e32 v101, 0xffff0000, v111
	v_lshlrev_b32_e32 v102, 16, v112
	v_and_b32_e32 v103, 0xffff0000, v112
	v_pk_add_f32 v[120:121], v[94:95], v[106:107]
	v_pk_add_f32 v[122:123], v[92:93], v[104:105]
	v_lshlrev_b32_e32 v92, 16, v3
	v_and_b32_e32 v93, 0xffff0000, v3
	v_lshlrev_b32_e32 v94, 16, v108
	v_and_b32_e32 v95, 0xffff0000, v108
	v_pk_add_f32 v[124:125], v[98:99], v[102:103]
	v_pk_add_f32 v[128:129], v[96:97], v[100:101]
	v_lshlrev_b32_e32 v96, 16, v109
	v_and_b32_e32 v97, 0xffff0000, v109
	v_pk_add_f32 v[116:117], v[90:91], v[94:95]
	v_pk_add_f32 v[118:119], v[88:89], v[92:93]
	v_lshlrev_b32_e32 v98, 16, v110
	v_and_b32_e32 v99, 0xffff0000, v110
	v_mul_f32_e32 v3, v129, v129
	v_mul_f32_e32 v100, v125, v125
	v_pk_add_f32 v[114:115], v[84:85], v[96:97]
	v_mul_f32_e32 v84, v119, v119
	v_mul_f32_e32 v85, v117, v117
	v_mul_f32_e32 v101, v123, v123
	v_pk_add_f32 v[112:113], v[86:87], v[98:99]
	v_fmac_f32_e32 v3, v128, v128
	v_fmac_f32_e32 v100, v124, v124
	v_mul_f32_e32 v86, v115, v115
	v_fmac_f32_e32 v84, v118, v118
	v_fmac_f32_e32 v85, v116, v116
	v_mul_f32_e32 v102, v121, v121
	v_fmac_f32_e32 v101, v122, v122
	v_mul_f32_e32 v87, v113, v113
	v_add_f32_e32 v3, v3, v100
	v_fmac_f32_e32 v86, v114, v114
	v_add_f32_e32 v84, v84, v85
	v_fmac_f32_e32 v102, v120, v120
	v_add_f32_e32 v3, v101, v3
	v_add_f32_e32 v84, v84, v86
	v_fmac_f32_e32 v87, v112, v112
	v_add_f32_e32 v3, v102, v3
	v_add_f32_e32 v84, v87, v84
	v_add_f32_e32 v3, v84, v3
	ds_bpermute_b32 v84, v169, v3
	s_waitcnt lgkmcnt(0)
	v_add_f32_e32 v84, v3, v84
	ds_bpermute_b32 v85, v171, v84
	v_mov_b32_e32 v3, 0
	s_and_saveexec_b64 s[4:5], vcc
	s_cbranch_execz .LBB0_1382
	s_waitcnt lgkmcnt(0)
	v_add_f32_e32 v84, v84, v85
	ds_write_b32 v170, v84 offset:512
.LBB0_1382:
	s_or_b64 exec, exec, s[4:5]
	v_or_b32_e32 v84, 48, v166
	s_waitcnt lgkmcnt(0)
	v_ashrrev_i32_e32 v85, 31, v84
	v_lshlrev_b64 v[84:85], 11, v[84:85]
	v_lshl_add_u64 v[84:85], s[42:43], 0, v[84:85]
	v_lshl_add_u64 v[84:85], v[0:1], 1, v[84:85]
	v_lshl_add_u64 v[86:87], v[84:85], 0, v[162:163]
	v_lshl_add_u64 v[88:89], v[84:85], 0, v[164:165]
	global_load_dwordx4 v[84:87], v[86:87], off nt
	s_nop 0
	global_load_dwordx4 v[88:91], v[88:89], off nt
	v_mov_b32_e32 v92, 0
	v_mov_b32_e32 v93, 0
	v_mov_b32_e32 v94, 0
	s_waitcnt vmcnt(0)
	v_cndmask_b32_e64 v95, v88, v84, s[2:3]
	v_cndmask_b32_e64 v96, v89, v85, s[2:3]
	v_cndmask_b32_e64 v97, v90, v86, s[2:3]
	v_cndmask_b32_e64 v98, v91, v87, s[2:3]
	v_cndmask_b32_e64 v84, v84, v88, s[2:3]
	v_cndmask_b32_e64 v85, v85, v89, s[2:3]
	v_cndmask_b32_e64 v86, v86, v90, s[2:3]
	v_cndmask_b32_e64 v87, v87, v91, s[2:3]
	v_mov_b32_dpp v92, v84 row_ror:8 row_mask:0xf bank_mask:0xf
	v_mov_b32_dpp v93, v85 row_ror:8 row_mask:0xf bank_mask:0xf
	v_lshlrev_b32_e32 v88, 16, v97
	v_and_b32_e32 v89, 0xffff0000, v97
	v_lshlrev_b32_e32 v90, 16, v98
	v_and_b32_e32 v91, 0xffff0000, v98
	v_mov_b32_dpp v94, v86 row_ror:8 row_mask:0xf bank_mask:0xf
	v_mov_b32_dpp v3, v87 row_ror:8 row_mask:0xf bank_mask:0xf
	v_lshlrev_b32_e32 v84, 16, v95
	v_and_b32_e32 v85, 0xffff0000, v95
	v_lshlrev_b32_e32 v86, 16, v96
	v_and_b32_e32 v87, 0xffff0000, v96
	v_pk_add_f32 v[104:105], v[78:79], v[90:91]
	v_pk_add_f32 v[106:107], v[76:77], v[88:89]
	v_lshlrev_b32_e32 v76, 16, v92
	v_and_b32_e32 v77, 0xffff0000, v92
	v_lshlrev_b32_e32 v78, 16, v93
	v_and_b32_e32 v79, 0xffff0000, v93
	v_pk_add_f32 v[108:109], v[82:83], v[86:87]
	v_pk_add_f32 v[110:111], v[80:81], v[84:85]
	v_lshlrev_b32_e32 v80, 16, v94
	v_and_b32_e32 v81, 0xffff0000, v94
	v_pk_add_f32 v[100:101], v[74:75], v[78:79]
	v_pk_add_f32 v[102:103], v[72:73], v[76:77]
	v_lshlrev_b32_e32 v82, 16, v3
	v_and_b32_e32 v83, 0xffff0000, v3
	v_mul_f32_e32 v3, v111, v111
	v_mul_f32_e32 v84, v109, v109
	v_pk_add_f32 v[98:99], v[68:69], v[80:81]
	v_mul_f32_e32 v68, v103, v103
	v_mul_f32_e32 v69, v101, v101
	v_mul_f32_e32 v85, v107, v107
	v_pk_add_f32 v[94:95], v[70:71], v[82:83]
	v_fmac_f32_e32 v3, v110, v110
	v_fmac_f32_e32 v84, v108, v108
	v_mul_f32_e32 v70, v99, v99
	v_fmac_f32_e32 v68, v102, v102
	v_fmac_f32_e32 v69, v100, v100
	v_mul_f32_e32 v86, v105, v105
	v_fmac_f32_e32 v85, v106, v106
	v_mul_f32_e32 v71, v95, v95
	v_add_f32_e32 v3, v3, v84
	v_fmac_f32_e32 v70, v98, v98
	v_add_f32_e32 v68, v68, v69
	v_fmac_f32_e32 v86, v104, v104
	v_add_f32_e32 v3, v85, v3
	v_add_f32_e32 v68, v68, v70
	v_fmac_f32_e32 v71, v94, v94
	v_add_f32_e32 v3, v86, v3
	v_add_f32_e32 v68, v71, v68
	v_add_f32_e32 v3, v68, v3
	ds_bpermute_b32 v68, v169, v3
	s_waitcnt lgkmcnt(0)
	v_add_f32_e32 v3, v3, v68
	ds_bpermute_b32 v68, v171, v3
	s_and_saveexec_b64 s[4:5], vcc
	s_cbranch_execz .LBB0_1384
	s_waitcnt lgkmcnt(0)
	v_add_f32_e32 v3, v3, v68
	ds_write_b32 v170, v3 offset:768
.LBB0_1384:
	s_or_b64 exec, exec, s[4:5]
	s_waitcnt lgkmcnt(0)
	v_lshlrev_b64 v[68:69], 11, v[166:167]
	v_lshl_add_u64 v[68:69], s[42:43], 0, v[68:69]
	v_lshl_add_u64 v[68:69], v[0:1], 1, v[68:69]
	s_mov_b64 s[4:5], 0x40000
	v_lshl_add_u64 v[70:71], v[68:69], 0, s[4:5]
	v_lshl_add_u64 v[72:73], v[70:71], 0, v[162:163]
	v_lshl_add_u64 v[74:75], v[70:71], 0, v[164:165]
	global_load_dwordx4 v[70:73], v[72:73], off nt
	s_nop 0
	global_load_dwordx4 v[74:77], v[74:75], off nt
	v_mov_b32_e32 v3, 0
	v_mov_b32_e32 v78, 0
	v_mov_b32_e32 v79, 0
	v_mov_b32_e32 v80, 0
	s_waitcnt vmcnt(0)
	v_cndmask_b32_e64 v81, v74, v70, s[2:3]
	v_cndmask_b32_e64 v82, v75, v71, s[2:3]
	v_cndmask_b32_e64 v83, v76, v72, s[2:3]
	v_cndmask_b32_e64 v84, v77, v73, s[2:3]
	v_cndmask_b32_e64 v70, v70, v74, s[2:3]
	v_cndmask_b32_e64 v71, v71, v75, s[2:3]
	v_cndmask_b32_e64 v72, v72, v76, s[2:3]
	v_cndmask_b32_e64 v73, v73, v77, s[2:3]
	v_mov_b32_dpp v3, v70 row_ror:8 row_mask:0xf bank_mask:0xf
	v_mov_b32_dpp v78, v71 row_ror:8 row_mask:0xf bank_mask:0xf
	v_lshlrev_b32_e32 v74, 16, v83
	v_and_b32_e32 v75, 0xffff0000, v83
	v_lshlrev_b32_e32 v76, 16, v84
	v_and_b32_e32 v77, 0xffff0000, v84
	v_mov_b32_dpp v79, v72 row_ror:8 row_mask:0xf bank_mask:0xf
	v_mov_b32_dpp v80, v73 row_ror:8 row_mask:0xf bank_mask:0xf
	v_lshlrev_b32_e32 v70, 16, v81
	v_and_b32_e32 v71, 0xffff0000, v81
	v_lshlrev_b32_e32 v72, 16, v82
	v_and_b32_e32 v73, 0xffff0000, v82
	v_pk_add_f32 v[88:89], v[62:63], v[76:77]
	v_pk_add_f32 v[90:91], v[60:61], v[74:75]
	v_lshlrev_b32_e32 v60, 16, v3
	v_and_b32_e32 v61, 0xffff0000, v3
	v_lshlrev_b32_e32 v62, 16, v78
	v_and_b32_e32 v63, 0xffff0000, v78
	v_pk_add_f32 v[92:93], v[66:67], v[72:73]
	v_pk_add_f32 v[96:97], v[64:65], v[70:71]
	v_lshlrev_b32_e32 v64, 16, v79
	v_and_b32_e32 v65, 0xffff0000, v79
	v_pk_add_f32 v[84:85], v[58:59], v[62:63]
	v_pk_add_f32 v[86:87], v[56:57], v[60:61]
	v_lshlrev_b32_e32 v66, 16, v80
	v_and_b32_e32 v67, 0xffff0000, v80
	v_mul_f32_e32 v3, v97, v97
	v_mul_f32_e32 v70, v93, v93
	v_pk_add_f32 v[82:83], v[52:53], v[64:65]
	v_mul_f32_e32 v52, v87, v87
	v_mul_f32_e32 v53, v85, v85
	v_mul_f32_e32 v71, v91, v91
	v_pk_add_f32 v[80:81], v[54:55], v[66:67]
	v_fmac_f32_e32 v3, v96, v96
	v_fmac_f32_e32 v70, v92, v92
	v_mul_f32_e32 v54, v83, v83
	v_fmac_f32_e32 v52, v86, v86
	v_fmac_f32_e32 v53, v84, v84
	v_mul_f32_e32 v72, v89, v89
	v_fmac_f32_e32 v71, v90, v90
	v_mul_f32_e32 v55, v81, v81
	v_add_f32_e32 v3, v3, v70
	v_fmac_f32_e32 v54, v82, v82
	v_add_f32_e32 v52, v52, v53
	v_fmac_f32_e32 v72, v88, v88
	v_add_f32_e32 v3, v71, v3
	v_add_f32_e32 v52, v52, v54
	v_fmac_f32_e32 v55, v80, v80
	v_add_f32_e32 v3, v72, v3
	v_add_f32_e32 v52, v55, v52
	v_add_f32_e32 v3, v52, v3
	ds_bpermute_b32 v52, v169, v3
	s_waitcnt lgkmcnt(0)
	v_add_f32_e32 v53, v3, v52
	ds_bpermute_b32 v54, v171, v53
	v_add_u32_e32 v3, 0x80, v168
	v_mov_b32_e32 v52, 0
	s_and_saveexec_b64 s[4:5], vcc
	s_cbranch_execz .LBB0_1386
	v_lshl_add_u32 v55, v3, 4, s6
	s_waitcnt lgkmcnt(0)
	v_add_f32_e32 v53, v53, v54
	ds_write_b32 v55, v53
.LBB0_1386:
	s_or_b64 exec, exec, s[4:5]
	s_mov_b64 s[4:5], 0x48000
	s_waitcnt lgkmcnt(0)
	v_lshl_add_u64 v[54:55], v[68:69], 0, s[4:5]
	v_lshl_add_u64 v[56:57], v[54:55], 0, v[162:163]
	v_lshl_add_u64 v[58:59], v[54:55], 0, v[164:165]
	global_load_dwordx4 v[54:57], v[56:57], off nt
	s_nop 0
	global_load_dwordx4 v[58:61], v[58:59], off nt
	v_mov_b32_e32 v53, 0
	v_mov_b32_e32 v62, 0
	v_mov_b32_e32 v63, 0
	s_waitcnt vmcnt(0)
	v_cndmask_b32_e64 v64, v58, v54, s[2:3]
	v_cndmask_b32_e64 v65, v59, v55, s[2:3]
	v_cndmask_b32_e64 v66, v60, v56, s[2:3]
	v_cndmask_b32_e64 v67, v61, v57, s[2:3]
	v_cndmask_b32_e64 v54, v54, v58, s[2:3]
	v_cndmask_b32_e64 v55, v55, v59, s[2:3]
	v_cndmask_b32_e64 v56, v56, v60, s[2:3]
	v_cndmask_b32_e64 v57, v57, v61, s[2:3]
	v_mov_b32_dpp v53, v54 row_ror:8 row_mask:0xf bank_mask:0xf
	v_mov_b32_dpp v62, v55 row_ror:8 row_mask:0xf bank_mask:0xf
	v_lshlrev_b32_e32 v58, 16, v66
	v_and_b32_e32 v59, 0xffff0000, v66
	v_lshlrev_b32_e32 v60, 16, v67
	v_and_b32_e32 v61, 0xffff0000, v67
	v_mov_b32_dpp v63, v56 row_ror:8 row_mask:0xf bank_mask:0xf
	v_mov_b32_dpp v52, v57 row_ror:8 row_mask:0xf bank_mask:0xf
	v_lshlrev_b32_e32 v54, 16, v64
	v_and_b32_e32 v55, 0xffff0000, v64
	v_lshlrev_b32_e32 v56, 16, v65
	v_and_b32_e32 v57, 0xffff0000, v65
	v_pk_add_f32 v[72:73], v[46:47], v[60:61]
	v_pk_add_f32 v[74:75], v[44:45], v[58:59]
	v_lshlrev_b32_e32 v44, 16, v53
	v_and_b32_e32 v45, 0xffff0000, v53
	v_lshlrev_b32_e32 v46, 16, v62
	v_and_b32_e32 v47, 0xffff0000, v62
	v_pk_add_f32 v[76:77], v[50:51], v[56:57]
	v_pk_add_f32 v[78:79], v[48:49], v[54:55]
	v_lshlrev_b32_e32 v48, 16, v63
	v_and_b32_e32 v49, 0xffff0000, v63
	v_pk_add_f32 v[68:69], v[42:43], v[46:47]
	v_pk_add_f32 v[70:71], v[40:41], v[44:45]
	v_lshlrev_b32_e32 v50, 16, v52
	v_and_b32_e32 v51, 0xffff0000, v52
	v_mul_f32_e32 v52, v79, v79
	v_mul_f32_e32 v53, v77, v77
	v_pk_add_f32 v[66:67], v[36:37], v[48:49]
	v_mul_f32_e32 v36, v71, v71
	v_mul_f32_e32 v37, v69, v69
	v_mul_f32_e32 v54, v75, v75
	v_pk_add_f32 v[62:63], v[38:39], v[50:51]
	v_fmac_f32_e32 v52, v78, v78
	v_fmac_f32_e32 v53, v76, v76
	v_mul_f32_e32 v38, v67, v67
	v_fmac_f32_e32 v36, v70, v70
	v_fmac_f32_e32 v37, v68, v68
	v_mul_f32_e32 v55, v73, v73
	v_fmac_f32_e32 v54, v74, v74
	v_mul_f32_e32 v39, v63, v63
	v_add_f32_e32 v40, v52, v53
	v_fmac_f32_e32 v38, v66, v66
	v_add_f32_e32 v36, v36, v37
	v_fmac_f32_e32 v55, v72, v72
	v_add_f32_e32 v40, v54, v40
	v_add_f32_e32 v36, v36, v38
	v_fmac_f32_e32 v39, v62, v62
	v_add_f32_e32 v37, v55, v40
	v_add_f32_e32 v36, v39, v36
	v_add_f32_e32 v36, v36, v37
	ds_bpermute_b32 v37, v169, v36
	s_waitcnt lgkmcnt(0)
	v_add_f32_e32 v36, v36, v37
	ds_bpermute_b32 v37, v171, v36
	s_and_saveexec_b64 s[4:5], vcc
	s_cbranch_execz .LBB0_1388
	s_waitcnt lgkmcnt(0)
	v_add_f32_e32 v36, v36, v37
	ds_write_b32 v170, v36 offset:2304
.LBB0_1388:
	s_or_b64 exec, exec, s[4:5]
	s_waitcnt lgkmcnt(0)
	v_lshlrev_b64 v[36:37], 11, v[166:167]
	v_lshl_add_u64 v[36:37], s[42:43], 0, v[36:37]
	v_lshl_add_u64 v[36:37], v[0:1], 1, v[36:37]
	s_mov_b64 s[4:5], 0x50000
	v_lshl_add_u64 v[38:39], v[36:37], 0, s[4:5]
	v_lshl_add_u64 v[40:41], v[38:39], 0, v[162:163]
	v_lshl_add_u64 v[42:43], v[38:39], 0, v[164:165]
	global_load_dwordx4 v[38:41], v[40:41], off nt
	s_nop 0
	global_load_dwordx4 v[42:45], v[42:43], off nt
	v_mov_b32_e32 v46, 0
	v_mov_b32_e32 v47, 0
	v_mov_b32_e32 v48, 0
	v_mov_b32_e32 v49, 0
	s_waitcnt vmcnt(0)
	v_cndmask_b32_e64 v50, v42, v38, s[2:3]
	v_cndmask_b32_e64 v51, v43, v39, s[2:3]
	v_cndmask_b32_e64 v52, v44, v40, s[2:3]
	v_cndmask_b32_e64 v53, v45, v41, s[2:3]
	v_cndmask_b32_e64 v38, v38, v42, s[2:3]
	v_cndmask_b32_e64 v39, v39, v43, s[2:3]
	v_cndmask_b32_e64 v40, v40, v44, s[2:3]
	v_cndmask_b32_e64 v41, v41, v45, s[2:3]
	v_mov_b32_dpp v46, v38 row_ror:8 row_mask:0xf bank_mask:0xf
	v_mov_b32_dpp v47, v39 row_ror:8 row_mask:0xf bank_mask:0xf
	v_lshlrev_b32_e32 v42, 16, v52
	v_and_b32_e32 v43, 0xffff0000, v52
	v_lshlrev_b32_e32 v44, 16, v53
	v_and_b32_e32 v45, 0xffff0000, v53
	v_mov_b32_dpp v48, v40 row_ror:8 row_mask:0xf bank_mask:0xf
	v_mov_b32_dpp v49, v41 row_ror:8 row_mask:0xf bank_mask:0xf
	v_lshlrev_b32_e32 v38, 16, v50
	v_and_b32_e32 v39, 0xffff0000, v50
	v_lshlrev_b32_e32 v40, 16, v51
	v_and_b32_e32 v41, 0xffff0000, v51
	v_pk_add_f32 v[56:57], v[30:31], v[44:45]
	v_pk_add_f32 v[58:59], v[28:29], v[42:43]
	v_lshlrev_b32_e32 v28, 16, v46
	v_and_b32_e32 v29, 0xffff0000, v46
	v_lshlrev_b32_e32 v30, 16, v47
	v_and_b32_e32 v31, 0xffff0000, v47
	v_pk_add_f32 v[60:61], v[34:35], v[40:41]
	v_pk_add_f32 v[64:65], v[32:33], v[38:39]
	v_lshlrev_b32_e32 v32, 16, v48
	v_and_b32_e32 v33, 0xffff0000, v48
	v_pk_add_f32 v[52:53], v[26:27], v[30:31]
	v_pk_add_f32 v[54:55], v[24:25], v[28:29]
	v_lshlrev_b32_e32 v34, 16, v49
	v_and_b32_e32 v35, 0xffff0000, v49
	v_mul_f32_e32 v38, v65, v65
	v_mul_f32_e32 v39, v61, v61
	v_pk_add_f32 v[50:51], v[20:21], v[32:33]
	v_mul_f32_e32 v20, v55, v55
	v_mul_f32_e32 v21, v53, v53
	v_mul_f32_e32 v40, v59, v59
	v_pk_add_f32 v[48:49], v[22:23], v[34:35]
	v_fmac_f32_e32 v38, v64, v64
	v_fmac_f32_e32 v39, v60, v60
	v_mul_f32_e32 v22, v51, v51
	v_fmac_f32_e32 v20, v54, v54
	v_fmac_f32_e32 v21, v52, v52
	v_mul_f32_e32 v41, v57, v57
	v_fmac_f32_e32 v40, v58, v58
	v_mul_f32_e32 v23, v49, v49
	v_add_f32_e32 v24, v38, v39
	v_fmac_f32_e32 v22, v50, v50
	v_add_f32_e32 v20, v20, v21
	v_fmac_f32_e32 v41, v56, v56
	v_add_f32_e32 v24, v40, v24
	v_add_f32_e32 v20, v20, v22
	v_fmac_f32_e32 v23, v48, v48
	v_add_f32_e32 v21, v41, v24
	v_add_f32_e32 v20, v23, v20
	v_add_f32_e32 v20, v20, v21
	ds_bpermute_b32 v21, v169, v20
	s_waitcnt lgkmcnt(0)
	v_add_f32_e32 v21, v20, v21
	ds_bpermute_b32 v22, v171, v21
	v_mov_b32_e32 v20, 0
	s_and_saveexec_b64 s[4:5], vcc
	s_cbranch_execz .LBB0_1390
	s_waitcnt lgkmcnt(0)
	v_add_f32_e32 v21, v21, v22
	ds_write_b32 v170, v21 offset:2560
.LBB0_1390:
	s_or_b64 exec, exec, s[4:5]
	s_mov_b64 s[4:5], 0x58000
	s_waitcnt lgkmcnt(0)
	v_lshl_add_u64 v[22:23], v[36:37], 0, s[4:5]
	v_lshl_add_u64 v[24:25], v[22:23], 0, v[162:163]
	v_lshl_add_u64 v[26:27], v[22:23], 0, v[164:165]
	global_load_dwordx4 v[22:25], v[24:25], off nt
	s_nop 0
	global_load_dwordx4 v[26:29], v[26:27], off nt
	v_mov_b32_e32 v21, 0
	v_mov_b32_e32 v30, 0
	v_mov_b32_e32 v31, 0
	s_waitcnt vmcnt(0)
	v_cndmask_b32_e64 v32, v26, v22, s[2:3]
	v_cndmask_b32_e64 v33, v27, v23, s[2:3]
	v_cndmask_b32_e64 v34, v28, v24, s[2:3]
	v_cndmask_b32_e64 v35, v29, v25, s[2:3]
	v_cndmask_b32_e64 v22, v22, v26, s[2:3]
	v_cndmask_b32_e64 v23, v23, v27, s[2:3]
	v_cndmask_b32_e64 v24, v24, v28, s[2:3]
	v_cndmask_b32_e64 v25, v25, v29, s[2:3]
	v_mov_b32_dpp v21, v22 row_ror:8 row_mask:0xf bank_mask:0xf
	v_mov_b32_dpp v30, v23 row_ror:8 row_mask:0xf bank_mask:0xf
	v_lshlrev_b32_e32 v26, 16, v34
	v_and_b32_e32 v27, 0xffff0000, v34
	v_lshlrev_b32_e32 v28, 16, v35
	v_and_b32_e32 v29, 0xffff0000, v35
	v_mov_b32_dpp v31, v24 row_ror:8 row_mask:0xf bank_mask:0xf
	v_mov_b32_dpp v20, v25 row_ror:8 row_mask:0xf bank_mask:0xf
	v_lshlrev_b32_e32 v22, 16, v32
	v_and_b32_e32 v23, 0xffff0000, v32
	v_lshlrev_b32_e32 v24, 16, v33
	v_and_b32_e32 v25, 0xffff0000, v33
	v_pk_add_f32 v[40:41], v[14:15], v[28:29]
	v_pk_add_f32 v[42:43], v[12:13], v[26:27]
	v_lshlrev_b32_e32 v12, 16, v21
	v_and_b32_e32 v13, 0xffff0000, v21
	v_lshlrev_b32_e32 v14, 16, v30
	v_and_b32_e32 v15, 0xffff0000, v30
	v_pk_add_f32 v[44:45], v[18:19], v[24:25]
	v_pk_add_f32 v[46:47], v[16:17], v[22:23]
	v_lshlrev_b32_e32 v16, 16, v31
	v_and_b32_e32 v17, 0xffff0000, v31
	v_pk_add_f32 v[36:37], v[10:11], v[14:15]
	v_pk_add_f32 v[38:39], v[8:9], v[12:13]
	v_lshlrev_b32_e32 v18, 16, v20
	v_and_b32_e32 v19, 0xffff0000, v20
	v_mul_f32_e32 v20, v47, v47
	v_mul_f32_e32 v21, v45, v45
	v_pk_add_f32 v[34:35], v[4:5], v[16:17]
	v_mul_f32_e32 v4, v39, v39
	v_mul_f32_e32 v5, v37, v37
	v_mul_f32_e32 v22, v43, v43
	v_pk_add_f32 v[32:33], v[6:7], v[18:19]
	v_fmac_f32_e32 v20, v46, v46
	v_fmac_f32_e32 v21, v44, v44
	v_mul_f32_e32 v6, v35, v35
	v_fmac_f32_e32 v4, v38, v38
	v_fmac_f32_e32 v5, v36, v36
	v_mul_f32_e32 v23, v41, v41
	v_fmac_f32_e32 v22, v42, v42
	v_mul_f32_e32 v7, v33, v33
	v_add_f32_e32 v8, v20, v21
	v_fmac_f32_e32 v6, v34, v34
	v_add_f32_e32 v4, v4, v5
	v_fmac_f32_e32 v23, v40, v40
	v_add_f32_e32 v8, v22, v8
	v_add_f32_e32 v4, v4, v6
	v_fmac_f32_e32 v7, v32, v32
	v_add_f32_e32 v5, v23, v8
	v_add_f32_e32 v4, v7, v4
	v_add_f32_e32 v4, v4, v5
	ds_bpermute_b32 v5, v169, v4
	s_waitcnt lgkmcnt(0)
	v_add_f32_e32 v4, v4, v5
	ds_bpermute_b32 v5, v171, v4
	s_and_saveexec_b64 s[4:5], vcc
	s_cbranch_execz .LBB0_1392
	s_waitcnt lgkmcnt(0)
	v_add_f32_e32 v4, v4, v5
	ds_write_b32 v170, v4 offset:2816
